# nt hint also on the prologue's one-time f32 input-row loads
# speedup vs baseline: 1.0043x; 1.0043x over previous
; #define LAS __attribute__((address_space(3)))
; __device__ __forceinline__ void tr_item(const float* W, int ldn, int k0, int n0, const float* ks, const float* ns, bf16_t* WT, size_t dld, int rbase, int rstride, int dcol0, LAS float* scr, int lane) {
;     f32x4 v[8];
; #pragma unroll
;     for (int i = 0; i < 8; ++i) v[i] = *(const f32x4*)(W + (size_t)(k0 + 8 * i + (lane >> 3)) * ldn + n0 + 4 * (lane & 7));
; #pragma unroll
;     for (int i = 0; i < 8; ++i) { const int kk = 8 * i + (lane >> 3); const float s = ks ? ks[k0 + kk] : 1.0f; LAS float* d = scr + kk * 33 + 4 * (lane & 7);
;         d[0] = v[i][0] * s; d[1] = v[i][1] * s; d[2] = v[i][2] * s; d[3] = v[i][3] * s; }
.LBB0_75:
	s_lshl_b32 s30, s62, 6
	v_add_u32_e32 v42, s30, v34
	v_mad_u64_u32 v[2:3], s[4:5], v42, s14, 0
	v_ashrrev_i32_e32 v43, 31, v42
	v_mov_b32_e32 v4, v3
	v_mad_u64_u32 v[4:5], s[4:5], v43, s14, v[4:5]
	v_mov_b32_e32 v3, v4
	v_add_u32_e32 v4, 8, v42
	v_ashrrev_i32_e32 v7, 31, v4
	v_mad_u64_u32 v[4:5], s[4:5], v4, s14, 0
	s_ashr_i32 s3, s2, 31
	v_mov_b32_e32 v6, v5
	v_lshl_add_u64 v[0:1], s[2:3], 2, v[40:41]
	v_mad_u64_u32 v[6:7], s[4:5], v7, s14, v[6:7]
	v_lshl_add_u64 v[2:3], v[2:3], 2, v[0:1]
	v_mov_b32_e32 v5, v6
	v_lshl_add_u64 v[4:5], v[4:5], 2, v[0:1]
	global_load_dwordx4 v[28:31], v[2:3], off nt
	global_load_dwordx4 v[24:27], v[4:5], off nt
	v_add_u32_e32 v2, 16, v42
	v_ashrrev_i32_e32 v5, 31, v2
	v_mad_u64_u32 v[2:3], s[4:5], v2, s14, 0
	v_mov_b32_e32 v4, v3
	v_mad_u64_u32 v[4:5], s[4:5], v5, s14, v[4:5]
	v_mov_b32_e32 v3, v4
	v_add_u32_e32 v4, 24, v42
	v_ashrrev_i32_e32 v7, 31, v4
	v_mad_u64_u32 v[4:5], s[4:5], v4, s14, 0
	v_mov_b32_e32 v6, v5
	v_mad_u64_u32 v[6:7], s[4:5], v7, s14, v[6:7]
	v_lshl_add_u64 v[2:3], v[2:3], 2, v[0:1]
	v_mov_b32_e32 v5, v6
	v_lshl_add_u64 v[4:5], v[4:5], 2, v[0:1]
	global_load_dwordx4 v[20:23], v[2:3], off nt
	global_load_dwordx4 v[16:19], v[4:5], off nt
	v_add_u32_e32 v2, 32, v42
	v_ashrrev_i32_e32 v5, 31, v2
	v_mad_u64_u32 v[2:3], s[4:5], v2, s14, 0
	v_mov_b32_e32 v4, v3
	v_mad_u64_u32 v[4:5], s[4:5], v5, s14, v[4:5]
	v_mov_b32_e32 v3, v4
	v_add_u32_e32 v4, 40, v42
	v_ashrrev_i32_e32 v7, 31, v4
	v_mad_u64_u32 v[4:5], s[4:5], v4, s14, 0
	v_mov_b32_e32 v6, v5
	v_mad_u64_u32 v[6:7], s[4:5], v7, s14, v[6:7]
	v_lshl_add_u64 v[2:3], v[2:3], 2, v[0:1]
	v_mov_b32_e32 v5, v6
	v_lshl_add_u64 v[4:5], v[4:5], 2, v[0:1]
	global_load_dwordx4 v[12:15], v[2:3], off nt
	global_load_dwordx4 v[8:11], v[4:5], off nt
	v_add_u32_e32 v2, 48, v42
	v_ashrrev_i32_e32 v5, 31, v2
	v_mad_u64_u32 v[2:3], s[4:5], v2, s14, 0
	v_mov_b32_e32 v4, v3
	v_mad_u64_u32 v[4:5], s[4:5], v5, s14, v[4:5]
	v_mov_b32_e32 v3, v4
	v_add_u32_e32 v4, 56, v42
	v_ashrrev_i32_e32 v7, 31, v4
	v_mad_u64_u32 v[4:5], s[4:5], v4, s14, 0
	v_mov_b32_e32 v6, v5
	v_mad_u64_u32 v[6:7], s[4:5], v7, s14, v[6:7]
	v_mov_b32_e32 v5, v6
	v_lshl_add_u64 v[2:3], v[2:3], 2, v[0:1]
	v_lshl_add_u64 v[0:1], v[4:5], 2, v[0:1]
	global_load_dwordx4 v[4:7], v[2:3], off nt
	s_nop 0
	global_load_dwordx4 v[0:3], v[0:1], off nt
	v_mov_b32_e32 v44, 1.0
	v_cmp_ne_u32_e64 s[4:5], 1, v39
	s_andn2_b64 vcc, exec, s[24:25]
	v_mov_b32_e32 v46, 1.0
	s_cbranch_vccnz .LBB0_77
	s_ashr_i32 s31, s30, 31
	v_lshl_add_u64 v[42:43], v[42:43], 2, s[18:19]
	v_lshl_add_u64 v[50:51], s[30:31], 0, v[34:35]
	global_load_dword v42, v[42:43], off
	v_lshl_add_u64 v[50:51], v[50:51], 2, s[18:19]
	global_load_dword v46, v[50:51], off offset:32
	s_waitcnt vmcnt(1)
	v_pk_mul_f32 v[28:29], v[28:29], v[42:43] op_sel_hi:[1,0]
	v_pk_mul_f32 v[30:31], v[30:31], v[42:43] op_sel_hi:[1,0]

; template <class T> __device__ __forceinline__ T* as_global(T* p) { return (T*)(T GAS*)(unsigned long long)p; }
; __device__ __forceinline__ void p0_prologue(const Frame& F, KArgs* A_k) {
;     ...
;     for (int r0 = gw; r0 < MT; r0 += 3 * NGW) {
;         f32x4 v[3][8];
; #pragma unroll
;         for (int k = 0; k < 3; ++k) { const int r = r0 + k * NGW; if (r < MT) {
;             const float* xr = r < MP ? as_global(A_k->in[I_XP]) + (size_t)r * DM : as_global(A_k->in[I_XS]) + (size_t)(r - MP) * DM;
; #pragma unroll
;             for (int j = 0; j < 8; ++j) v[k][j] = *(const f32x4*)(xr + (64 * j + lane) * 4); } }
.LBB0_116:
	s_add_i32 s16, s6, 0xffffc000
	s_cmpk_lt_i32 s6, 0x4000
	s_cselect_b32 s18, 0, 8
	s_cselect_b32 s17, s7, 0
	s_cselect_b32 s16, s6, s16
	s_add_u32 s18, s0, s18
	s_addc_u32 s19, s1, 0
	s_load_dwordx2 s[18:19], s[18:19], 0x0
	s_lshl_b64 s[16:17], s[16:17], 13
	s_waitcnt lgkmcnt(0)
	s_add_u32 s16, s18, s16
	s_addc_u32 s17, s19, s17
	v_lshl_add_u64 v[64:65], v[96:97], 2, s[16:17]
	global_load_dwordx4 v[92:95], v[64:65], off nt
	global_load_dwordx4 v[88:91], v[64:65], off offset:1024 nt
	global_load_dwordx4 v[84:87], v[64:65], off offset:2048 nt
	global_load_dwordx4 v[80:83], v[64:65], off offset:3072 nt
	v_lshl_add_u64 v[64:65], v[98:99], 2, s[16:17]
	v_lshl_add_u64 v[66:67], v[100:101], 2, s[16:17]
	v_lshl_add_u64 v[114:115], v[102:103], 2, s[16:17]
	global_load_dwordx4 v[76:79], v[64:65], off nt
	global_load_dwordx4 v[72:75], v[66:67], off nt
	v_lshl_add_u64 v[116:117], v[104:105], 2, s[16:17]
	global_load_dwordx4 v[68:71], v[114:115], off nt
	global_load_dwordx4 v[64:67], v[116:117], off nt
	s_add_u32 s18, s8, s6
	s_cmpk_lt_i32 s18, 0x4800
	s_cselect_b64 s[22:23], -1, 0
	s_cmpk_gt_i32 s18, 0x47ff
	s_cbranch_scc1 .LBB0_118
	s_ashr_i32 s16, s18, 31
	s_add_i32 s19, s18, 0xffffc000
	s_cmpk_lt_i32 s18, 0x4000
	s_cselect_b32 s17, s16, 0
	s_cselect_b32 s16, s18, s19
	s_cselect_b32 s19, 0, 8
	s_add_u32 s20, s0, s19
	s_addc_u32 s21, s1, 0
	s_load_dwordx2 s[20:21], s[20:21], 0x0
	s_lshl_b64 s[16:17], s[16:17], 13
	s_waitcnt lgkmcnt(0)
	s_add_u32 s16, s20, s16
	s_addc_u32 s17, s21, s17
	v_lshl_add_u64 v[48:49], v[96:97], 2, s[16:17]
	global_load_dwordx4 v[36:39], v[48:49], off nt
	global_load_dwordx4 v[32:35], v[48:49], off offset:1024 nt
	global_load_dwordx4 v[28:31], v[48:49], off offset:2048 nt
	global_load_dwordx4 v[24:27], v[48:49], off offset:3072 nt
	v_lshl_add_u64 v[56:57], v[98:99], 2, s[16:17]
	v_lshl_add_u64 v[58:59], v[100:101], 2, s[16:17]
	v_lshl_add_u64 v[114:115], v[102:103], 2, s[16:17]
	global_load_dwordx4 v[52:55], v[56:57], off nt
	global_load_dwordx4 v[48:51], v[58:59], off nt
	v_lshl_add_u64 v[116:117], v[104:105], 2, s[16:17]
	global_load_dwordx4 v[60:63], v[114:115], off nt
	global_load_dwordx4 v[56:59], v[116:117], off nt
.LBB0_118:
	s_add_u32 s16, s29, s6
	s_cmpk_lt_i32 s16, 0x4800
	s_cselect_b64 s[20:21], -1, 0
	s_cmpk_gt_i32 s16, 0x47ff
	s_cbranch_scc1 .LBB0_120
	s_ashr_i32 s17, s16, 31
	s_add_i32 s19, s16, 0xffffc000
	s_cmpk_lt_i32 s16, 0x4000
	s_cselect_b32 s25, s17, 0
	s_cselect_b32 s17, 0, 8
	s_cselect_b32 s24, s16, s19
	s_add_u32 s34, s0, s17
	s_addc_u32 s35, s1, 0
	s_load_dwordx2 s[34:35], s[34:35], 0x0
	s_lshl_b64 s[24:25], s[24:25], 13
	s_waitcnt lgkmcnt(0)
	s_add_u32 s24, s34, s24
	s_addc_u32 s25, s35, s25
	v_lshl_add_u64 v[16:17], v[96:97], 2, s[24:25]
	global_load_dwordx4 v[12:15], v[16:17], off nt
	global_load_dwordx4 v[8:11], v[16:17], off offset:1024 nt
	global_load_dwordx4 v[4:7], v[16:17], off offset:2048 nt
	global_load_dwordx4 v[0:3], v[16:17], off offset:3072 nt
	v_lshl_add_u64 v[40:41], v[98:99], 2, s[24:25]
	v_lshl_add_u64 v[42:43], v[100:101], 2, s[24:25]
	v_lshl_add_u64 v[114:115], v[102:103], 2, s[24:25]
	global_load_dwordx4 v[20:23], v[40:41], off nt
	global_load_dwordx4 v[16:19], v[42:43], off nt
	v_lshl_add_u64 v[116:117], v[104:105], 2, s[24:25]
	global_load_dwordx4 v[44:47], v[114:115], off nt
	global_load_dwordx4 v[40:43], v[116:117], off nt

; #define LAS __attribute__((address_space(3)))
; __device__ __forceinline__ void tr_item(const float* W, int ldn, int k0, int n0, const float* ks, const float* ns, bf16_t* WT, size_t dld, int rbase, int rstride, int dcol0, LAS float* scr, int lane) {
;     f32x4 v[8];
; #pragma unroll
;     for (int i = 0; i < 8; ++i) v[i] = *(const f32x4*)(W + (size_t)(k0 + 8 * i + (lane >> 3)) * ldn + n0 + 4 * (lane & 7));
; #pragma unroll
;     for (int i = 0; i < 8; ++i) { const int kk = 8 * i + (lane >> 3); const float s = ks ? ks[k0 + kk] : 1.0f; LAS float* d = scr + kk * 33 + 4 * (lane & 7);
;         d[0] = v[i][0] * s; d[1] = v[i][1] * s; d[2] = v[i][2] * s; d[3] = v[i][3] * s; }
.LBB0_515:
	s_lshl_b32 s24, s63, 6
	v_add_u32_e32 v42, s24, v34
	v_mad_u64_u32 v[4:5], s[2:3], v42, s51, 0
	v_ashrrev_i32_e32 v43, 31, v42
	v_mov_b32_e32 v6, v5
	v_mad_u64_u32 v[6:7], s[2:3], v43, s51, v[6:7]
	v_mov_b32_e32 v5, v6
	v_add_u32_e32 v6, 8, v42
	v_ashrrev_i32_e32 v9, 31, v6
	v_mad_u64_u32 v[6:7], s[2:3], v6, s51, 0
	s_ashr_i32 s21, s20, 31
	v_mov_b32_e32 v8, v7
	v_lshl_add_u64 v[2:3], s[20:21], 2, v[38:39]
	v_mad_u64_u32 v[8:9], s[2:3], v9, s51, v[8:9]
	v_lshl_add_u64 v[4:5], v[4:5], 2, v[2:3]
	v_mov_b32_e32 v7, v8
	v_lshl_add_u64 v[6:7], v[6:7], 2, v[2:3]
	global_load_dwordx4 v[30:33], v[4:5], off nt
	global_load_dwordx4 v[26:29], v[6:7], off nt
	v_add_u32_e32 v4, 16, v42
	v_ashrrev_i32_e32 v7, 31, v4
	v_mad_u64_u32 v[4:5], s[2:3], v4, s51, 0
	v_mov_b32_e32 v6, v5
	v_mad_u64_u32 v[6:7], s[2:3], v7, s51, v[6:7]
	v_mov_b32_e32 v5, v6
	v_add_u32_e32 v6, 24, v42
	v_ashrrev_i32_e32 v9, 31, v6
	v_mad_u64_u32 v[6:7], s[2:3], v6, s51, 0
	v_mov_b32_e32 v8, v7
	v_mad_u64_u32 v[8:9], s[2:3], v9, s51, v[8:9]
	v_lshl_add_u64 v[4:5], v[4:5], 2, v[2:3]
	v_mov_b32_e32 v7, v8
	v_lshl_add_u64 v[6:7], v[6:7], 2, v[2:3]
	global_load_dwordx4 v[22:25], v[4:5], off nt
	global_load_dwordx4 v[18:21], v[6:7], off nt
	v_add_u32_e32 v4, 32, v42
	v_ashrrev_i32_e32 v7, 31, v4
	v_mad_u64_u32 v[4:5], s[2:3], v4, s51, 0
	v_mov_b32_e32 v6, v5
	v_mad_u64_u32 v[6:7], s[2:3], v7, s51, v[6:7]
	v_mov_b32_e32 v5, v6
	v_add_u32_e32 v6, 40, v42
	v_ashrrev_i32_e32 v9, 31, v6
	v_mad_u64_u32 v[6:7], s[2:3], v6, s51, 0
	v_mov_b32_e32 v8, v7
	v_mad_u64_u32 v[8:9], s[2:3], v9, s51, v[8:9]
	v_lshl_add_u64 v[4:5], v[4:5], 2, v[2:3]
	v_mov_b32_e32 v7, v8
	v_lshl_add_u64 v[6:7], v[6:7], 2, v[2:3]
	global_load_dwordx4 v[14:17], v[4:5], off nt
	global_load_dwordx4 v[10:13], v[6:7], off nt
	v_add_u32_e32 v4, 48, v42
	v_ashrrev_i32_e32 v7, 31, v4
	v_mad_u64_u32 v[4:5], s[2:3], v4, s51, 0
	v_mov_b32_e32 v6, v5
	v_mad_u64_u32 v[6:7], s[2:3], v7, s51, v[6:7]
	v_mov_b32_e32 v5, v6
	v_add_u32_e32 v6, 56, v42
	v_ashrrev_i32_e32 v9, 31, v6
	v_mad_u64_u32 v[6:7], s[2:3], v6, s51, 0
	v_mov_b32_e32 v8, v7
	v_mad_u64_u32 v[8:9], s[2:3], v9, s51, v[8:9]
	v_mov_b32_e32 v7, v8
	v_lshl_add_u64 v[4:5], v[4:5], 2, v[2:3]
	v_lshl_add_u64 v[2:3], v[6:7], 2, v[2:3]
	global_load_dwordx4 v[6:9], v[4:5], off nt
	s_nop 0
	global_load_dwordx4 v[2:5], v[2:3], off nt
	v_cndmask_b32_e64 v44, 0, 1, s[16:17]
	v_mov_b32_e32 v40, 1.0
	v_cmp_ne_u32_e64 s[4:5], 1, v44
	s_andn2_b64 vcc, exec, s[16:17]
	v_mov_b32_e32 v44, 1.0
	s_cbranch_vccnz .LBB0_517
	v_lshl_add_u64 v[42:43], v[42:43], 2, s[10:11]
	global_load_dword v42, v[42:43], off
	s_ashr_i32 s25, s24, 31
	s_waitcnt vmcnt(0)
	v_pk_mul_f32 v[30:31], v[30:31], v[42:43] op_sel_hi:[1,0]
	v_pk_mul_f32 v[32:33], v[32:33], v[42:43] op_sel_hi:[1,0]
	v_lshl_add_u64 v[42:43], s[24:25], 0, v[34:35]
	v_lshl_add_u64 v[42:43], v[42:43], 2, s[10:11]
	global_load_dword v44, v[42:43], off offset:32

; #define LAS __attribute__((address_space(3)))
; __device__ __forceinline__ void tr_item(const float* W, int ldn, int k0, int n0, const float* ks, const float* ns, bf16_t* WT, size_t dld, int rbase, int rstride, int dcol0, LAS float* scr, int lane) {
;     f32x4 v[8];
; #pragma unroll
;     for (int i = 0; i < 8; ++i) v[i] = *(const f32x4*)(W + (size_t)(k0 + 8 * i + (lane >> 3)) * ldn + n0 + 4 * (lane & 7));
; #pragma unroll
;     for (int i = 0; i < 8; ++i) { const int kk = 8 * i + (lane >> 3); const float s = ks ? ks[k0 + kk] : 1.0f; LAS float* d = scr + kk * 33 + 4 * (lane & 7);
;         d[0] = v[i][0] * s; d[1] = v[i][1] * s; d[2] = v[i][2] * s; d[3] = v[i][3] * s; }
.LBB0_616:
	s_lshl_b32 s24, s60, 6
	v_add_u32_e32 v42, s24, v34
	v_mad_u64_u32 v[4:5], s[2:3], v42, s50, 0
	v_ashrrev_i32_e32 v43, 31, v42
	v_mov_b32_e32 v6, v5
	v_mad_u64_u32 v[6:7], s[2:3], v43, s50, v[6:7]
	v_mov_b32_e32 v5, v6
	v_add_u32_e32 v6, 8, v42
	v_ashrrev_i32_e32 v9, 31, v6
	v_mad_u64_u32 v[6:7], s[2:3], v6, s50, 0
	s_ashr_i32 s21, s20, 31
	v_mov_b32_e32 v8, v7
	v_lshl_add_u64 v[2:3], s[20:21], 2, v[38:39]
	v_mad_u64_u32 v[8:9], s[2:3], v9, s50, v[8:9]
	v_lshl_add_u64 v[4:5], v[4:5], 2, v[2:3]
	v_mov_b32_e32 v7, v8
	v_lshl_add_u64 v[6:7], v[6:7], 2, v[2:3]
	global_load_dwordx4 v[30:33], v[4:5], off nt
	global_load_dwordx4 v[26:29], v[6:7], off nt
	v_add_u32_e32 v4, 16, v42
	v_ashrrev_i32_e32 v7, 31, v4
	v_mad_u64_u32 v[4:5], s[2:3], v4, s50, 0
	v_mov_b32_e32 v6, v5
	v_mad_u64_u32 v[6:7], s[2:3], v7, s50, v[6:7]
	v_mov_b32_e32 v5, v6
	v_add_u32_e32 v6, 24, v42
	v_ashrrev_i32_e32 v9, 31, v6
	v_mad_u64_u32 v[6:7], s[2:3], v6, s50, 0
	v_mov_b32_e32 v8, v7
	v_mad_u64_u32 v[8:9], s[2:3], v9, s50, v[8:9]
	v_lshl_add_u64 v[4:5], v[4:5], 2, v[2:3]
	v_mov_b32_e32 v7, v8
	v_lshl_add_u64 v[6:7], v[6:7], 2, v[2:3]
	global_load_dwordx4 v[22:25], v[4:5], off nt
	global_load_dwordx4 v[18:21], v[6:7], off nt
	v_add_u32_e32 v4, 32, v42
	v_ashrrev_i32_e32 v7, 31, v4
	v_mad_u64_u32 v[4:5], s[2:3], v4, s50, 0
	v_mov_b32_e32 v6, v5
	v_mad_u64_u32 v[6:7], s[2:3], v7, s50, v[6:7]
	v_mov_b32_e32 v5, v6
	v_add_u32_e32 v6, 40, v42
	v_ashrrev_i32_e32 v9, 31, v6
	v_mad_u64_u32 v[6:7], s[2:3], v6, s50, 0
	v_mov_b32_e32 v8, v7
	v_mad_u64_u32 v[8:9], s[2:3], v9, s50, v[8:9]
	v_lshl_add_u64 v[4:5], v[4:5], 2, v[2:3]
	v_mov_b32_e32 v7, v8
	v_lshl_add_u64 v[6:7], v[6:7], 2, v[2:3]
	global_load_dwordx4 v[14:17], v[4:5], off nt
	global_load_dwordx4 v[10:13], v[6:7], off nt
	v_add_u32_e32 v4, 48, v42
	v_ashrrev_i32_e32 v7, 31, v4
	v_mad_u64_u32 v[4:5], s[2:3], v4, s50, 0
	v_mov_b32_e32 v6, v5
	v_mad_u64_u32 v[6:7], s[2:3], v7, s50, v[6:7]
	v_mov_b32_e32 v5, v6
	v_add_u32_e32 v6, 56, v42
	v_ashrrev_i32_e32 v9, 31, v6
	v_mad_u64_u32 v[6:7], s[2:3], v6, s50, 0
	v_mov_b32_e32 v8, v7
	v_mad_u64_u32 v[8:9], s[2:3], v9, s50, v[8:9]
	v_mov_b32_e32 v7, v8
	v_lshl_add_u64 v[4:5], v[4:5], 2, v[2:3]
	v_lshl_add_u64 v[2:3], v[6:7], 2, v[2:3]
	global_load_dwordx4 v[6:9], v[4:5], off nt
	s_nop 0
	global_load_dwordx4 v[2:5], v[2:3], off nt
	v_cndmask_b32_e64 v44, 0, 1, s[16:17]
	v_mov_b32_e32 v40, 1.0
	v_cmp_ne_u32_e64 s[4:5], 1, v44
	s_andn2_b64 vcc, exec, s[16:17]
	v_mov_b32_e32 v44, 1.0
	s_cbranch_vccnz .LBB0_618
	v_lshl_add_u64 v[42:43], v[42:43], 2, s[10:11]
	global_load_dword v42, v[42:43], off
	s_ashr_i32 s25, s24, 31
	s_waitcnt vmcnt(0)
	v_pk_mul_f32 v[30:31], v[30:31], v[42:43] op_sel_hi:[1,0]
	v_pk_mul_f32 v[32:33], v[32:33], v[42:43] op_sel_hi:[1,0]
	v_lshl_add_u64 v[42:43], s[24:25], 0, v[34:35]
	v_lshl_add_u64 v[42:43], v[42:43], 2, s[10:11]
	global_load_dword v44, v[42:43], off offset:32

; #define LAS __attribute__((address_space(3)))
; __device__ __forceinline__ void tr_item(const float* W, int ldn, int k0, int n0, const float* ks, const float* ns, bf16_t* WT, size_t dld, int rbase, int rstride, int dcol0, LAS float* scr, int lane) {
;     f32x4 v[8];
; #pragma unroll
;     for (int i = 0; i < 8; ++i) v[i] = *(const f32x4*)(W + (size_t)(k0 + 8 * i + (lane >> 3)) * ldn + n0 + 4 * (lane & 7));
; #pragma unroll
;     for (int i = 0; i < 8; ++i) { const int kk = 8 * i + (lane >> 3); const float s = ks ? ks[k0 + kk] : 1.0f; LAS float* d = scr + kk * 33 + 4 * (lane & 7);
;         d[0] = v[i][0] * s; d[1] = v[i][1] * s; d[2] = v[i][2] * s; d[3] = v[i][3] * s; }
.LBB0_1938:
	s_lshl_b32 s26, s63, 6
	v_add_u32_e32 v42, s26, v34
	v_mad_u64_u32 v[4:5], s[2:3], v42, s51, 0
	v_ashrrev_i32_e32 v43, 31, v42
	v_mov_b32_e32 v6, v5
	v_mad_u64_u32 v[6:7], s[2:3], v43, s51, v[6:7]
	v_mov_b32_e32 v5, v6
	v_add_u32_e32 v6, 8, v42
	v_ashrrev_i32_e32 v9, 31, v6
	v_mad_u64_u32 v[6:7], s[2:3], v6, s51, 0
	s_ashr_i32 s23, s22, 31
	v_mov_b32_e32 v8, v7
	v_lshl_add_u64 v[2:3], s[22:23], 2, v[38:39]
	v_mad_u64_u32 v[8:9], s[2:3], v9, s51, v[8:9]
	v_lshl_add_u64 v[4:5], v[4:5], 2, v[2:3]
	v_mov_b32_e32 v7, v8
	v_lshl_add_u64 v[6:7], v[6:7], 2, v[2:3]
	global_load_dwordx4 v[30:33], v[4:5], off nt
	global_load_dwordx4 v[26:29], v[6:7], off nt
	v_add_u32_e32 v4, 16, v42
	v_ashrrev_i32_e32 v7, 31, v4
	v_mad_u64_u32 v[4:5], s[2:3], v4, s51, 0
	v_mov_b32_e32 v6, v5
	v_mad_u64_u32 v[6:7], s[2:3], v7, s51, v[6:7]
	v_mov_b32_e32 v5, v6
	v_add_u32_e32 v6, 24, v42
	v_ashrrev_i32_e32 v9, 31, v6
	v_mad_u64_u32 v[6:7], s[2:3], v6, s51, 0
	v_mov_b32_e32 v8, v7
	v_mad_u64_u32 v[8:9], s[2:3], v9, s51, v[8:9]
	v_lshl_add_u64 v[4:5], v[4:5], 2, v[2:3]
	v_mov_b32_e32 v7, v8
	v_lshl_add_u64 v[6:7], v[6:7], 2, v[2:3]
	global_load_dwordx4 v[22:25], v[4:5], off nt
	global_load_dwordx4 v[18:21], v[6:7], off nt
	v_add_u32_e32 v4, 32, v42
	v_ashrrev_i32_e32 v7, 31, v4
	v_mad_u64_u32 v[4:5], s[2:3], v4, s51, 0
	v_mov_b32_e32 v6, v5
	v_mad_u64_u32 v[6:7], s[2:3], v7, s51, v[6:7]
	v_mov_b32_e32 v5, v6
	v_add_u32_e32 v6, 40, v42
	v_ashrrev_i32_e32 v9, 31, v6
	v_mad_u64_u32 v[6:7], s[2:3], v6, s51, 0
	v_mov_b32_e32 v8, v7
	v_mad_u64_u32 v[8:9], s[2:3], v9, s51, v[8:9]
	v_lshl_add_u64 v[4:5], v[4:5], 2, v[2:3]
	v_mov_b32_e32 v7, v8
	v_lshl_add_u64 v[6:7], v[6:7], 2, v[2:3]
	global_load_dwordx4 v[14:17], v[4:5], off nt
	global_load_dwordx4 v[10:13], v[6:7], off nt
	v_add_u32_e32 v4, 48, v42
	v_ashrrev_i32_e32 v7, 31, v4
	v_mad_u64_u32 v[4:5], s[2:3], v4, s51, 0
	v_mov_b32_e32 v6, v5
	v_mad_u64_u32 v[6:7], s[2:3], v7, s51, v[6:7]
	v_mov_b32_e32 v5, v6
	v_add_u32_e32 v6, 56, v42
	v_ashrrev_i32_e32 v9, 31, v6
	v_mad_u64_u32 v[6:7], s[2:3], v6, s51, 0
	v_mov_b32_e32 v8, v7
	v_mad_u64_u32 v[8:9], s[2:3], v9, s51, v[8:9]
	v_mov_b32_e32 v7, v8
	v_lshl_add_u64 v[4:5], v[4:5], 2, v[2:3]
	v_lshl_add_u64 v[2:3], v[6:7], 2, v[2:3]
	global_load_dwordx4 v[6:9], v[4:5], off nt
	s_nop 0
	global_load_dwordx4 v[2:5], v[2:3], off nt
	v_cndmask_b32_e64 v44, 0, 1, s[18:19]
	v_mov_b32_e32 v40, 1.0
	v_cmp_ne_u32_e64 s[6:7], 1, v44
	s_andn2_b64 vcc, exec, s[18:19]
	v_mov_b32_e32 v44, 1.0
	s_cbranch_vccnz .LBB0_1940
	v_lshl_add_u64 v[42:43], v[42:43], 2, s[12:13]
	global_load_dword v42, v[42:43], off
	s_ashr_i32 s27, s26, 31
	s_waitcnt vmcnt(0)
	v_pk_mul_f32 v[30:31], v[30:31], v[42:43] op_sel_hi:[1,0]
	v_pk_mul_f32 v[32:33], v[32:33], v[42:43] op_sel_hi:[1,0]
	v_lshl_add_u64 v[42:43], s[26:27], 0, v[34:35]
	v_lshl_add_u64 v[42:43], v[42:43], 2, s[12:13]
	global_load_dword v44, v[42:43], off offset:32

; #define LAS __attribute__((address_space(3)))
; __device__ __forceinline__ void tr_item(const float* W, int ldn, int k0, int n0, const float* ks, const float* ns, bf16_t* WT, size_t dld, int rbase, int rstride, int dcol0, LAS float* scr, int lane) {
;     f32x4 v[8];
; #pragma unroll
;     for (int i = 0; i < 8; ++i) v[i] = *(const f32x4*)(W + (size_t)(k0 + 8 * i + (lane >> 3)) * ldn + n0 + 4 * (lane & 7));
; #pragma unroll
;     for (int i = 0; i < 8; ++i) { const int kk = 8 * i + (lane >> 3); const float s = ks ? ks[k0 + kk] : 1.0f; LAS float* d = scr + kk * 33 + 4 * (lane & 7);
;         d[0] = v[i][0] * s; d[1] = v[i][1] * s; d[2] = v[i][2] * s; d[3] = v[i][3] * s; }
.LBB0_2029:
	s_lshl_b32 s26, s60, 6
	v_add_u32_e32 v42, s26, v34
	v_mad_u64_u32 v[4:5], s[2:3], v42, s50, 0
	v_ashrrev_i32_e32 v43, 31, v42
	v_mov_b32_e32 v6, v5
	v_mad_u64_u32 v[6:7], s[2:3], v43, s50, v[6:7]
	v_mov_b32_e32 v5, v6
	v_add_u32_e32 v6, 8, v42
	v_ashrrev_i32_e32 v9, 31, v6
	v_mad_u64_u32 v[6:7], s[2:3], v6, s50, 0
	s_ashr_i32 s23, s22, 31
	v_mov_b32_e32 v8, v7
	v_lshl_add_u64 v[2:3], s[22:23], 2, v[38:39]
	v_mad_u64_u32 v[8:9], s[2:3], v9, s50, v[8:9]
	v_lshl_add_u64 v[4:5], v[4:5], 2, v[2:3]
	v_mov_b32_e32 v7, v8
	v_lshl_add_u64 v[6:7], v[6:7], 2, v[2:3]
	global_load_dwordx4 v[30:33], v[4:5], off nt
	global_load_dwordx4 v[26:29], v[6:7], off nt
	v_add_u32_e32 v4, 16, v42
	v_ashrrev_i32_e32 v7, 31, v4
	v_mad_u64_u32 v[4:5], s[2:3], v4, s50, 0
	v_mov_b32_e32 v6, v5
	v_mad_u64_u32 v[6:7], s[2:3], v7, s50, v[6:7]
	v_mov_b32_e32 v5, v6
	v_add_u32_e32 v6, 24, v42
	v_ashrrev_i32_e32 v9, 31, v6
	v_mad_u64_u32 v[6:7], s[2:3], v6, s50, 0
	v_mov_b32_e32 v8, v7
	v_mad_u64_u32 v[8:9], s[2:3], v9, s50, v[8:9]
	v_lshl_add_u64 v[4:5], v[4:5], 2, v[2:3]
	v_mov_b32_e32 v7, v8
	v_lshl_add_u64 v[6:7], v[6:7], 2, v[2:3]
	global_load_dwordx4 v[22:25], v[4:5], off nt
	global_load_dwordx4 v[18:21], v[6:7], off nt
	v_add_u32_e32 v4, 32, v42
	v_ashrrev_i32_e32 v7, 31, v4
	v_mad_u64_u32 v[4:5], s[2:3], v4, s50, 0
	v_mov_b32_e32 v6, v5
	v_mad_u64_u32 v[6:7], s[2:3], v7, s50, v[6:7]
	v_mov_b32_e32 v5, v6
	v_add_u32_e32 v6, 40, v42
	v_ashrrev_i32_e32 v9, 31, v6
	v_mad_u64_u32 v[6:7], s[2:3], v6, s50, 0
	v_mov_b32_e32 v8, v7
	v_mad_u64_u32 v[8:9], s[2:3], v9, s50, v[8:9]
	v_lshl_add_u64 v[4:5], v[4:5], 2, v[2:3]
	v_mov_b32_e32 v7, v8
	v_lshl_add_u64 v[6:7], v[6:7], 2, v[2:3]
	global_load_dwordx4 v[14:17], v[4:5], off nt
	global_load_dwordx4 v[10:13], v[6:7], off nt
	v_add_u32_e32 v4, 48, v42
	v_ashrrev_i32_e32 v7, 31, v4
	v_mad_u64_u32 v[4:5], s[2:3], v4, s50, 0
	v_mov_b32_e32 v6, v5
	v_mad_u64_u32 v[6:7], s[2:3], v7, s50, v[6:7]
	v_mov_b32_e32 v5, v6
	v_add_u32_e32 v6, 56, v42
	v_ashrrev_i32_e32 v9, 31, v6
	v_mad_u64_u32 v[6:7], s[2:3], v6, s50, 0
	v_mov_b32_e32 v8, v7
	v_mad_u64_u32 v[8:9], s[2:3], v9, s50, v[8:9]
	v_mov_b32_e32 v7, v8
	v_lshl_add_u64 v[4:5], v[4:5], 2, v[2:3]
	v_lshl_add_u64 v[2:3], v[6:7], 2, v[2:3]
	global_load_dwordx4 v[6:9], v[4:5], off nt
	s_nop 0
	global_load_dwordx4 v[2:5], v[2:3], off nt
	v_cndmask_b32_e64 v44, 0, 1, s[18:19]
	v_mov_b32_e32 v40, 1.0
	v_cmp_ne_u32_e64 s[6:7], 1, v44
	s_andn2_b64 vcc, exec, s[18:19]
	v_mov_b32_e32 v44, 1.0
	s_cbranch_vccnz .LBB0_2031
	v_lshl_add_u64 v[42:43], v[42:43], 2, s[12:13]
	global_load_dword v42, v[42:43], off
	s_ashr_i32 s27, s26, 31
	s_waitcnt vmcnt(0)
	v_pk_mul_f32 v[30:31], v[30:31], v[42:43] op_sel_hi:[1,0]
	v_pk_mul_f32 v[32:33], v[32:33], v[42:43] op_sel_hi:[1,0]
	v_lshl_add_u64 v[42:43], s[26:27], 0, v[34:35]
	v_lshl_add_u64 v[42:43], v[42:43], 2, s[12:13]
	global_load_dword v44, v[42:43], off offset:32
